# rms_rows (FFN-norm): two-row software pipeline, next row's loads in flight during reduce/scale/store
# baseline (speedup 1.0000x reference)
; __device__ __forceinline__ void rms_rows(const Ctx& c, const float* x, const float* gain, bf16_t* out, float* xcopy) {
;     f32x4 gv[4];
; #pragma unroll
;     for (int j = 0; j < 4; ++j) gv[j] = ((const f32x4*)gain)[c.lane + 64 * j];
;     for (int m = c.gw; m < M_; m += c.ngw) {
;         const f32x4* xr = (const f32x4*)(x + (size_t)m * D_) + c.lane;
;         f32x4 v[4]; float s = 0.f;
; #pragma unroll
.LBB0_72:
	s_and_b64 vcc, exec, s[2:3]
	s_cbranch_vccz .LBB0_80
	s_cmp_gt_i32 s48, 0
	s_mov_b64 s[2:3], -1
	s_cbranch_scc0 .LBB0_78
	s_cmpk_gt_i32 s28, 0x7fff
	s_cbranch_scc1 .LBB0_77
	v_readlane_b32 s0, v255, 26
	v_readlane_b32 s1, v255, 27
	s_lshl_b64 s[2:3], s[0:1], 3
	v_readlane_b32 s0, v255, 15
	v_readlane_b32 s1, v255, 16
	s_add_u32 s2, s0, s2
	s_addc_u32 s3, s1, s3
	s_load_dwordx2 s[2:3], s[2:3], 0x18
	v_readlane_b32 s0, v255, 19
	s_lshl_b32 s42, s0, 10
	s_lshl_b64 s[6:7], s[42:43], 2
	v_ashrrev_i32_e32 v165, 31, v164
	s_waitcnt lgkmcnt(0)
	s_add_u32 s2, s2, s6
	v_lshlrev_b64 v[20:21], 4, v[164:165]
	s_addc_u32 s3, s3, s7
	v_lshl_add_u64 v[14:15], s[2:3], 0, v[20:21]
	global_load_dwordx4 v[2:5], v[14:15], off offset:3072
	global_load_dwordx4 v[6:9], v[14:15], off offset:2048
	global_load_dwordx4 v[10:13], v[14:15], off offset:1024
	s_nop 0
	global_load_dwordx4 v[14:17], v[14:15], off
	s_ashr_i32 s29, s28, 31
	s_lshl_b64 s[2:3], s[28:29], 11
	s_add_u32 s2, s74, s2
	s_addc_u32 s3, s75, s3
	s_ashr_i32 s31, s30, 31
	v_lshl_add_u64 v[18:19], v[164:165], 3, s[2:3]
	s_lshl_b64 s[2:3], s[30:31], 11
	s_lshl_b64 s[6:7], s[28:29], 12
	s_add_u32 s6, s66, s6
	s_addc_u32 s7, s67, s7
	s_movk_i32 s1, 0x2000
	v_lshl_add_u64 v[20:21], s[6:7], 0, v[20:21]
	s_lshl_b64 s[6:7], s[30:31], 12
	s_mov_b32 s10, s28
	global_load_dwordx4 v[22:25], v[20:21], off
	global_load_dwordx4 v[26:29], v[20:21], off offset:1024
	global_load_dwordx4 v[30:33], v[20:21], off offset:2048
	global_load_dwordx4 v[34:37], v[20:21], off offset:3072
	v_lshl_add_u64 v[20:21], v[20:21], 0, s[6:7]
.LBB0_76:

; __device__ __forceinline__ void rms_rows(const Ctx& c, const float* x, const float* gain, bf16_t* out, float* xcopy) {
;     ...
;     for (int m = c.gw; m < M_; m += c.ngw) {
;         const f32x4* xr = (const f32x4*)(x + (size_t)m * D_) + c.lane;
;         f32x4 v[4]; float s = 0.f;
; #pragma unroll
;         for (int j = 0; j < 4; ++j) { v[j] = xr[64 * j]; s += (v[j].x * v[j].x + v[j].y * v[j].y) + (v[j].z * v[j].z + v[j].w * v[j].w); }
	s_add_i32 s10, s10, s30
	s_cmpk_gt_i32 s10, 0x7fff
	s_cbranch_scc1 .Lrm_xl
	global_load_dwordx4 v[44:47], v[20:21], off
	global_load_dwordx4 v[48:51], v[20:21], off offset:1024
	global_load_dwordx4 v[52:55], v[20:21], off offset:2048
	global_load_dwordx4 v[56:59], v[20:21], off offset:3072
	v_lshl_add_u64 v[20:21], v[20:21], 0, s[6:7]
	s_waitcnt vmcnt(4)
	s_branch .Lrm_xc

; __device__ __forceinline__ unsigned pk2(float lo, float hi) { f32x2 v = {lo, hi}; bf16x2_t b = __builtin_convertvector(v, bf16x2_t); return __builtin_bit_cast(unsigned, b); }
; __device__ __forceinline__ float wave_sum_dpp(float v) { v = half32_sum(v); auto r = __builtin_amdgcn_permlane32_swap(asu(v), asu(v), false, false); return asf(r[0]) + asf(r[1]); }
; __device__ __forceinline__ void rms_rows(const Ctx& c, const float* x, const float* gain, bf16_t* out, float* xcopy) {
;     ...
;         for (int j = 0; j < 4; ++j) { v[j] = xr[64 * j]; s += (v[j].x * v[j].x + v[j].y * v[j].y) + (v[j].z * v[j].z + v[j].w * v[j].w); }
;         if (xcopy) { f32x4* xc = (f32x4*)(xcopy + (size_t)m * D_) + c.lane;
; #pragma unroll
;             for (int j = 0; j < 4; ++j) xc[64 * j] = v[j]; }
;         const float r = rsqrtf(wave_sum_dpp(s) * (1.f / D_) + 1e-6f);
;         u32x2* o8 = (u32x2*)(out + (size_t)m * D_) + c.lane;
; #pragma unroll
;         for (int j = 0; j < 4; ++j) { u32x2 w; w.x = pk2(v[j].x * r * gv[j].x, v[j].y * r * gv[j].y); w.y = pk2(v[j].z * r * gv[j].z, v[j].w * r * gv[j].w); o8[64 * j] = w; }
;     }
.Lrm_xc:
	v_mul_f32_e32 v1, v23, v23
	v_mul_f32_e32 v40, v25, v25
	v_fmac_f32_e32 v1, v22, v22
	v_fmac_f32_e32 v40, v24, v24
	v_add_f32_e32 v1, v1, v40
	v_mul_f32_e32 v40, v27, v27
	v_mul_f32_e32 v41, v29, v29
	v_fmac_f32_e32 v40, v26, v26
	v_fmac_f32_e32 v41, v28, v28
	v_add_f32_e32 v40, v40, v41
	v_add_f32_e32 v1, v1, v40
	v_mul_f32_e32 v40, v31, v31
	v_mul_f32_e32 v41, v33, v33
	v_fmac_f32_e32 v40, v30, v30
	v_fmac_f32_e32 v41, v32, v32
	v_add_f32_e32 v40, v40, v41
	v_add_f32_e32 v1, v1, v40
	v_mul_f32_e32 v38, v35, v35
	v_mul_f32_e32 v39, v37, v37
	v_fmac_f32_e32 v38, v34, v34
	v_fmac_f32_e32 v39, v36, v36
	v_add_f32_e32 v38, v38, v39
	v_add_f32_e32 v1, v1, v38
	s_nop 1
	v_add_f32_dpp v1, v1, v1 row_ror:8 row_mask:0xf bank_mask:0xf bound_ctrl:1
	s_nop 1
	v_add_f32_dpp v1, v1, v1 row_ror:4 row_mask:0xf bank_mask:0xf bound_ctrl:1
	s_nop 1
	v_add_f32_dpp v1, v1, v1 row_ror:2 row_mask:0xf bank_mask:0xf bound_ctrl:1
	s_nop 1
	v_add_f32_dpp v1, v1, v1 row_ror:1 row_mask:0xf bank_mask:0xf bound_ctrl:1
	v_mov_b32_e32 v38, v1
	s_nop 1
	v_permlane16_swap_b32_e32 v1, v38
	v_add_f32_e32 v1, v1, v38
	v_mov_b32_e32 v38, v1
	s_nop 1
	v_permlane32_swap_b32_e32 v1, v38
	v_add_f32_e32 v1, v1, v38
	v_fmamk_f32 v1, v1, 0x3a800000, v148
	v_cmp_gt_f32_e32 vcc, s33, v1
	v_mul_f32_e32 v38, 0x4b800000, v1
	s_nop 0
	v_cndmask_b32_e32 v1, v1, v38, vcc
	v_rsq_f32_e32 v1, v1
	s_nop 0
	v_mul_f32_e32 v38, 0x45800000, v1
	v_cndmask_b32_e32 v38, v1, v38, vcc
	v_pk_mul_f32 v[22:23], v[22:23], v[38:39] op_sel_hi:[1,0]
	v_pk_mul_f32 v[24:25], v[24:25], v[38:39] op_sel_hi:[1,0]
	v_pk_mul_f32 v[22:23], v[14:15], v[22:23]
	v_pk_mul_f32 v[24:25], v[16:17], v[24:25]
	v_cvt_pk_bf16_f32 v22, v22, v23
	v_cvt_pk_bf16_f32 v23, v24, v25
	global_store_dwordx2 v[18:19], v[22:23], off
	v_pk_mul_f32 v[22:23], v[26:27], v[38:39] op_sel_hi:[1,0]
	v_pk_mul_f32 v[24:25], v[28:29], v[38:39] op_sel_hi:[1,0]
	v_pk_mul_f32 v[22:23], v[10:11], v[22:23]
	v_pk_mul_f32 v[24:25], v[12:13], v[24:25]
	v_cvt_pk_bf16_f32 v22, v22, v23
	v_cvt_pk_bf16_f32 v23, v24, v25
	global_store_dwordx2 v[18:19], v[22:23], off offset:512
	v_pk_mul_f32 v[22:23], v[30:31], v[38:39] op_sel_hi:[1,0]
	v_pk_mul_f32 v[24:25], v[32:33], v[38:39] op_sel_hi:[1,0]
	v_pk_mul_f32 v[22:23], v[6:7], v[22:23]
	v_pk_mul_f32 v[24:25], v[8:9], v[24:25]
	v_cvt_pk_bf16_f32 v22, v22, v23
	v_cvt_pk_bf16_f32 v23, v24, v25
	global_store_dwordx2 v[18:19], v[22:23], off offset:1024
	v_pk_mul_f32 v[22:23], v[34:35], v[38:39] op_sel_hi:[1,0]
	v_pk_mul_f32 v[24:25], v[36:37], v[38:39] op_sel_hi:[1,0]
	v_pk_mul_f32 v[22:23], v[2:3], v[22:23]
	v_pk_mul_f32 v[24:25], v[4:5], v[24:25]
	v_cvt_pk_bf16_f32 v22, v22, v23
	v_cvt_pk_bf16_f32 v23, v24, v25
	global_store_dwordx2 v[18:19], v[22:23], off offset:1536
	v_lshl_add_u64 v[18:19], v[18:19], 0, s[2:3]
	s_cmpk_gt_i32 s10, 0x7fff
	s_cbranch_scc1 .Lrm_done
	s_add_i32 s10, s10, s30
	s_cmpk_gt_i32 s10, 0x7fff
	s_cbranch_scc1 .Lrm_yl
	global_load_dwordx4 v[22:25], v[20:21], off
	global_load_dwordx4 v[26:29], v[20:21], off offset:1024
	global_load_dwordx4 v[30:33], v[20:21], off offset:2048
	global_load_dwordx4 v[34:37], v[20:21], off offset:3072
	v_lshl_add_u64 v[20:21], v[20:21], 0, s[6:7]
	s_waitcnt vmcnt(4)
	s_branch .Lrm_yc

; __device__ __forceinline__ unsigned pk2(float lo, float hi) { f32x2 v = {lo, hi}; bf16x2_t b = __builtin_convertvector(v, bf16x2_t); return __builtin_bit_cast(unsigned, b); }
; __device__ __forceinline__ float wave_sum_dpp(float v) { v = half32_sum(v); auto r = __builtin_amdgcn_permlane32_swap(asu(v), asu(v), false, false); return asf(r[0]) + asf(r[1]); }
; __device__ __forceinline__ void rms_rows(const Ctx& c, const float* x, const float* gain, bf16_t* out, float* xcopy) {
;     ...
;         for (int j = 0; j < 4; ++j) { v[j] = xr[64 * j]; s += (v[j].x * v[j].x + v[j].y * v[j].y) + (v[j].z * v[j].z + v[j].w * v[j].w); }
;         if (xcopy) { f32x4* xc = (f32x4*)(xcopy + (size_t)m * D_) + c.lane;
; #pragma unroll
;             for (int j = 0; j < 4; ++j) xc[64 * j] = v[j]; }
;         const float r = rsqrtf(wave_sum_dpp(s) * (1.f / D_) + 1e-6f);
;         u32x2* o8 = (u32x2*)(out + (size_t)m * D_) + c.lane;
; #pragma unroll
;         for (int j = 0; j < 4; ++j) { u32x2 w; w.x = pk2(v[j].x * r * gv[j].x, v[j].y * r * gv[j].y); w.y = pk2(v[j].z * r * gv[j].z, v[j].w * r * gv[j].w); o8[64 * j] = w; }
;     }
.Lrm_yc:
	v_mul_f32_e32 v1, v45, v45
	v_mul_f32_e32 v40, v47, v47
	v_fmac_f32_e32 v1, v44, v44
	v_fmac_f32_e32 v40, v46, v46
	v_add_f32_e32 v1, v1, v40
	v_mul_f32_e32 v40, v49, v49
	v_mul_f32_e32 v41, v51, v51
	v_fmac_f32_e32 v40, v48, v48
	v_fmac_f32_e32 v41, v50, v50
	v_add_f32_e32 v40, v40, v41
	v_add_f32_e32 v1, v1, v40
	v_mul_f32_e32 v40, v53, v53
	v_mul_f32_e32 v41, v55, v55
	v_fmac_f32_e32 v40, v52, v52
	v_fmac_f32_e32 v41, v54, v54
	v_add_f32_e32 v40, v40, v41
	v_add_f32_e32 v1, v1, v40
	v_mul_f32_e32 v38, v57, v57
	v_mul_f32_e32 v39, v59, v59
	v_fmac_f32_e32 v38, v56, v56
	v_fmac_f32_e32 v39, v58, v58
	v_add_f32_e32 v38, v38, v39
	v_add_f32_e32 v1, v1, v38
	s_nop 1
	v_add_f32_dpp v1, v1, v1 row_ror:8 row_mask:0xf bank_mask:0xf bound_ctrl:1
	s_nop 1
	v_add_f32_dpp v1, v1, v1 row_ror:4 row_mask:0xf bank_mask:0xf bound_ctrl:1
	s_nop 1
	v_add_f32_dpp v1, v1, v1 row_ror:2 row_mask:0xf bank_mask:0xf bound_ctrl:1
	s_nop 1
	v_add_f32_dpp v1, v1, v1 row_ror:1 row_mask:0xf bank_mask:0xf bound_ctrl:1
	v_mov_b32_e32 v38, v1
	s_nop 1
	v_permlane16_swap_b32_e32 v1, v38
	v_add_f32_e32 v1, v1, v38
	v_mov_b32_e32 v38, v1
	s_nop 1
	v_permlane32_swap_b32_e32 v1, v38
	v_add_f32_e32 v1, v1, v38
	v_fmamk_f32 v1, v1, 0x3a800000, v148
	v_cmp_gt_f32_e32 vcc, s33, v1
	v_mul_f32_e32 v38, 0x4b800000, v1
	s_nop 0
	v_cndmask_b32_e32 v1, v1, v38, vcc
	v_rsq_f32_e32 v1, v1
	s_nop 0
	v_mul_f32_e32 v38, 0x45800000, v1
	v_cndmask_b32_e32 v38, v1, v38, vcc
	v_pk_mul_f32 v[44:45], v[44:45], v[38:39] op_sel_hi:[1,0]
	v_pk_mul_f32 v[46:47], v[46:47], v[38:39] op_sel_hi:[1,0]
	v_pk_mul_f32 v[44:45], v[14:15], v[44:45]
	v_pk_mul_f32 v[46:47], v[16:17], v[46:47]
	v_cvt_pk_bf16_f32 v44, v44, v45
	v_cvt_pk_bf16_f32 v45, v46, v47
	global_store_dwordx2 v[18:19], v[44:45], off
	v_pk_mul_f32 v[44:45], v[48:49], v[38:39] op_sel_hi:[1,0]
	v_pk_mul_f32 v[46:47], v[50:51], v[38:39] op_sel_hi:[1,0]
	v_pk_mul_f32 v[44:45], v[10:11], v[44:45]
	v_pk_mul_f32 v[46:47], v[12:13], v[46:47]
	v_cvt_pk_bf16_f32 v44, v44, v45
	v_cvt_pk_bf16_f32 v45, v46, v47
	global_store_dwordx2 v[18:19], v[44:45], off offset:512
	v_pk_mul_f32 v[44:45], v[52:53], v[38:39] op_sel_hi:[1,0]
	v_pk_mul_f32 v[46:47], v[54:55], v[38:39] op_sel_hi:[1,0]
	v_pk_mul_f32 v[44:45], v[6:7], v[44:45]
	v_pk_mul_f32 v[46:47], v[8:9], v[46:47]
	v_cvt_pk_bf16_f32 v44, v44, v45
	v_cvt_pk_bf16_f32 v45, v46, v47
	global_store_dwordx2 v[18:19], v[44:45], off offset:1024
	v_pk_mul_f32 v[44:45], v[56:57], v[38:39] op_sel_hi:[1,0]
	v_pk_mul_f32 v[46:47], v[58:59], v[38:39] op_sel_hi:[1,0]
	v_pk_mul_f32 v[44:45], v[2:3], v[44:45]
	v_pk_mul_f32 v[46:47], v[4:5], v[46:47]
	v_cvt_pk_bf16_f32 v44, v44, v45
	v_cvt_pk_bf16_f32 v45, v46, v47
	global_store_dwordx2 v[18:19], v[44:45], off offset:1536
	v_lshl_add_u64 v[18:19], v[18:19], 0, s[2:3]
	s_cmpk_gt_i32 s10, 0x7fff
	s_cbranch_scc0 .LBB0_76
.Lrm_done:
.LBB0_77:
	s_mov_b64 s[2:3], 0
